# rw_rkv and rg layer-1 weight transposes moved from the prologue to idle GEMM tails (register transpose per wave, non-temporal loads)
# speedup vs baseline: 1.0997x; 1.0013x over previous
; __device__ __forceinline__ void phase_prologue(KP P, const Ctx& c) {
;     ...
;     int rot = 0;
;     for (int j = 0; j < 2; ++j) {
;         tr_job(c, rot, P->in[I_RGWIN] + (size_t)j * D * 4096, D, 4096, 4096, (bf16_t*)(ws + WS_RGIN) + (size_t)j * 4096 * D, D, 0);
;         tr_job(c, rot, P->in[I_RGWOUT] + (size_t)j * D * D, D, D, D, (bf16_t*)(ws + WS_RGOUT) + (size_t)j * D * D, D, 0);
;     }
.LBB0_34:
	s_xor_b64 s[10:11], s[6:7], -1
	s_addk_i32 s25, 0x1800
	s_mov_b64 s[8:9], 1
	s_mov_b64 s[6:7], 0
	s_cmpk_lg_i32 s3, 0x100
	s_cbranch_scc1 .Lpro_rg_keep
	s_mov_b64 s[10:11], -1
.Lpro_rg_keep:
	s_and_b64 vcc, exec, s[10:11]
	s_cbranch_vccnz .LBB0_45

; #define LAS __attribute__((address_space(3)))
; #define TR_LOAD(it_) do { const int kb_ = (it_) / nblk, nb_ = (it_) % nblk; _Pragma("unroll") for (int i = 0; i < 8; ++i) r[i] = *(const f32x4*)(W + (size_t)(kb_ * 64 + 8 * i + (lane >> 3)) * ldw + nb_ * 32 + (lane & 7) * 4); } while (0)
; __device__ __forceinline__ void tr_job(const Ctx& c, int& rot, const float* W, int K, int N, int ldw, bf16_t* WT, int ldt, int row_off) {
;     LAS float* scr = (LAS float*)(c.lds + c.wave * 16384);
;     const int nblk = N / 32, items = (K / 64) * nblk;
;     int first = c.gw - (rot % c.ngw); if (first < 0) first += c.ngw;
;     int lane = c.lane; asm volatile("" : "+v"(lane));
;     f32x4 r[8];
;     ...
;     if (first < items) TR_LOAD(first);
; __device__ __forceinline__ void phase_prologue(KP P, const Ctx& c) {
;     ...
;     for (int m = 0; m < 3; ++m) tr_job(c, rot, P->in[I_RWRKV] + (size_t)m * D * D, D, D, D, (bf16_t*)(ws + WS_RW1), D, m * D);
.LBB0_48:
	s_mul_hi_u32 s6, s22, 0x3800
	s_add_u32 s8, s16, 0x7c00000
	s_mul_i32 s6, s6, s21
	s_addc_u32 s9, s17, 0
	s_sub_i32 s6, 0x3800, s6
	s_sub_i32 s7, s6, s21
	s_cmp_ge_u32 s6, s21
	s_cselect_b32 s6, s7, s6
	s_sub_i32 s7, s6, s21
	s_cmp_ge_u32 s6, s21
	s_cselect_b32 s6, s7, s6
	s_load_dwordx2 s[4:5], s[18:19], 0xa0
	s_sub_i32 s6, s20, s6
	s_ashr_i32 s7, s6, 31
	s_and_b32 s7, s7, s14
	s_add_i32 s10, s7, s6
	v_mov_b32_e32 v36, v1
	s_cmpk_lt_i32 s10, 0x800
	s_cbranch_scc0 .LBB0_53
	s_cmpk_eq_i32 s3, 0x100
	s_cbranch_scc1 .LBB0_53
	s_ashr_i32 s6, s10, 31
	s_lshr_b32 s6, s6, 26
	s_add_i32 s6, s10, s6
	s_andn2_b32 s6, s6, 63
	s_sub_i32 s7, s10, s6
	v_ashrrev_i32_e32 v38, 3, v36
	s_waitcnt vmcnt(5)
	v_add_u32_e32 v26, s6, v38
	s_lshl_b32 s6, s7, 5
	s_ashr_i32 s7, s6, 31
	s_lshl_b64 s[6:7], s[6:7], 2
	s_waitcnt lgkmcnt(0)
	s_add_u32 s6, s4, s6
	v_lshlrev_b32_e32 v2, 4, v36
	s_addc_u32 s7, s5, s7
	v_and_b32_e32 v40, 0x70, v2
	v_mov_b32_e32 v41, 0
	v_ashrrev_i32_e32 v27, 31, v26
	v_lshl_add_u64 v[28:29], s[6:7], 0, v[40:41]
	v_lshlrev_b64 v[2:3], 13, v[26:27]
	v_lshl_add_u64 v[10:11], v[28:29], 0, v[2:3]
	v_add_u32_e32 v2, 8, v26
	v_ashrrev_i32_e32 v3, 31, v2
	v_lshlrev_b64 v[2:3], 13, v[2:3]
	v_lshl_add_u64 v[12:13], v[28:29], 0, v[2:3]
	global_load_dwordx4 v[2:5], v[10:11], off
	global_load_dwordx4 v[6:9], v[12:13], off
	v_add_u32_e32 v10, 16, v26
	v_ashrrev_i32_e32 v11, 31, v10
	v_lshlrev_b64 v[10:11], 13, v[10:11]
	v_lshl_add_u64 v[18:19], v[28:29], 0, v[10:11]
	v_add_u32_e32 v10, 24, v26
	v_ashrrev_i32_e32 v11, 31, v10
	v_lshlrev_b64 v[10:11], 13, v[10:11]
	v_lshl_add_u64 v[20:21], v[28:29], 0, v[10:11]
	global_load_dwordx4 v[10:13], v[18:19], off
	global_load_dwordx4 v[14:17], v[20:21], off
	v_add_u32_e32 v18, 32, v26
	v_ashrrev_i32_e32 v19, 31, v18
	v_lshlrev_b64 v[18:19], 13, v[18:19]
	s_waitcnt vmcnt(8)
	v_lshl_add_u64 v[30:31], v[28:29], 0, v[18:19]
	v_add_u32_e32 v18, 40, v26
	v_ashrrev_i32_e32 v19, 31, v18
	v_lshlrev_b64 v[18:19], 13, v[18:19]
	v_lshl_add_u64 v[32:33], v[28:29], 0, v[18:19]
	global_load_dwordx4 v[18:21], v[30:31], off
	global_load_dwordx4 v[22:25], v[32:33], off
	v_add_u32_e32 v30, 48, v26
	v_ashrrev_i32_e32 v31, 31, v30
	v_add_u32_e32 v26, 56, v26
	v_lshlrev_b64 v[30:31], 13, v[30:31]
	v_ashrrev_i32_e32 v27, 31, v26
	v_lshl_add_u64 v[34:35], v[28:29], 0, v[30:31]
	v_lshlrev_b64 v[26:27], 13, v[26:27]
	v_lshl_add_u64 v[42:43], v[28:29], 0, v[26:27]
	global_load_dwordx4 v[26:29], v[34:35], off
	global_load_dwordx4 v[30:33], v[42:43], off
	v_lshlrev_b32_e32 v36, 3, v36
	v_and_b32_e32 v36, 56, v36
	v_add_u32_e32 v42, s15, v40
	v_lshl_add_u64 v[34:35], s[4:5], 0, v[40:41]
	v_lshlrev_b32_e32 v40, 1, v36
	s_movk_i32 s6, 0x84
	v_mul_u32_u24_e32 v39, 0x84, v36
	v_lshl_add_u64 v[36:37], s[8:9], 0, v[40:41]
	v_lshlrev_b32_e32 v40, 2, v38
	v_add3_u32 v39, s15, v39, v40
	v_mul_lo_u32 v40, v38, s6
	s_lshl_b32 s12, s14, 5
	s_lshl_b32 s11, s10, 5
	v_add_u32_e32 v40, v42, v40
	s_mov_b32 s13, s12
	v_mov_b32_e32 v41, v38
	s_branch .LBB0_51

; #define LAS __attribute__((address_space(3)))
; #define TR_LOAD(it_) do { const int kb_ = (it_) / nblk, nb_ = (it_) % nblk; _Pragma("unroll") for (int i = 0; i < 8; ++i) r[i] = *(const f32x4*)(W + (size_t)(kb_ * 64 + 8 * i + (lane >> 3)) * ldw + nb_ * 32 + (lane & 7) * 4); } while (0)
; __device__ __forceinline__ void tr_job(const Ctx& c, int& rot, const float* W, int K, int N, int ldw, bf16_t* WT, int ldt, int row_off) {
;     LAS float* scr = (LAS float*)(c.lds + c.wave * 16384);
;     const int nblk = N / 32, items = (K / 64) * nblk;
;     int first = c.gw - (rot % c.ngw); if (first < 0) first += c.ngw;
;     int lane = c.lane; asm volatile("" : "+v"(lane));
;     f32x4 r[8];
;     ...
;     if (first < items) TR_LOAD(first);
; __device__ __forceinline__ void phase_prologue(KP P, const Ctx& c) {
;     ...
;     for (int m = 0; m < 3; ++m) tr_job(c, rot, P->in[I_RWRKV] + (size_t)m * D * D, D, D, D, (bf16_t*)(ws + WS_RW1), D, m * D);
.LBB0_53:
	s_lshr_b32 s6, s22, 18
	s_mul_i32 s6, s6, s21
	s_sub_i32 s6, 0x4000, s6
	s_sub_i32 s7, s6, s21
	s_cmp_ge_u32 s6, s21
	s_cselect_b32 s6, s7, s6
	s_sub_i32 s7, s6, s21
	s_cmp_ge_u32 s6, s21
	s_cselect_b32 s6, s7, s6
	s_sub_i32 s6, s20, s6
	s_ashr_i32 s7, s6, 31
	s_and_b32 s7, s7, s14
	s_add_i32 s10, s7, s6
	v_mov_b32_e32 v36, v1
	s_cmpk_gt_i32 s10, 0x7ff
	s_cbranch_scc1 .LBB0_58
	s_cmpk_eq_i32 s3, 0x100
	s_cbranch_scc1 .LBB0_58
	s_waitcnt lgkmcnt(0)
	s_add_u32 s6, s4, 0x1000000
	s_addc_u32 s7, s5, 0
	s_ashr_i32 s11, s10, 31
	s_lshr_b32 s11, s11, 26
	s_add_i32 s11, s10, s11
	s_andn2_b32 s11, s11, 63
	s_sub_i32 s12, s10, s11
	s_lshl_b32 s12, s12, 5
	s_ashr_i32 s13, s12, 31
	v_ashrrev_i32_e32 v38, 3, v36
	s_lshl_b64 s[12:13], s[12:13], 2
	s_waitcnt vmcnt(5)
	v_add_u32_e32 v26, s11, v38
	s_add_u32 s12, s6, s12
	v_lshlrev_b32_e32 v2, 4, v36
	s_addc_u32 s13, s7, s13
	v_and_b32_e32 v40, 0x70, v2
	v_mov_b32_e32 v41, 0
	v_ashrrev_i32_e32 v27, 31, v26
	v_lshl_add_u64 v[28:29], s[12:13], 0, v[40:41]
	v_lshlrev_b64 v[2:3], 13, v[26:27]
	v_lshl_add_u64 v[10:11], v[28:29], 0, v[2:3]
	v_add_u32_e32 v2, 8, v26
	v_ashrrev_i32_e32 v3, 31, v2
	v_lshlrev_b64 v[2:3], 13, v[2:3]
	v_lshl_add_u64 v[12:13], v[28:29], 0, v[2:3]
	global_load_dwordx4 v[2:5], v[10:11], off
	global_load_dwordx4 v[6:9], v[12:13], off
	v_add_u32_e32 v10, 16, v26
	v_ashrrev_i32_e32 v11, 31, v10
	v_lshlrev_b64 v[10:11], 13, v[10:11]
	v_lshl_add_u64 v[18:19], v[28:29], 0, v[10:11]
	v_add_u32_e32 v10, 24, v26
	v_ashrrev_i32_e32 v11, 31, v10
	v_lshlrev_b64 v[10:11], 13, v[10:11]
	v_lshl_add_u64 v[20:21], v[28:29], 0, v[10:11]
	global_load_dwordx4 v[10:13], v[18:19], off
	global_load_dwordx4 v[14:17], v[20:21], off
	v_add_u32_e32 v18, 32, v26
	v_ashrrev_i32_e32 v19, 31, v18
	v_lshlrev_b64 v[18:19], 13, v[18:19]
	s_waitcnt vmcnt(8)
	v_lshl_add_u64 v[30:31], v[28:29], 0, v[18:19]
	v_add_u32_e32 v18, 40, v26
	v_ashrrev_i32_e32 v19, 31, v18
	v_lshlrev_b64 v[18:19], 13, v[18:19]
	v_lshl_add_u64 v[32:33], v[28:29], 0, v[18:19]
	global_load_dwordx4 v[18:21], v[30:31], off
	global_load_dwordx4 v[22:25], v[32:33], off
	v_add_u32_e32 v30, 48, v26
	v_ashrrev_i32_e32 v31, 31, v30
	v_add_u32_e32 v26, 56, v26
	v_lshlrev_b64 v[30:31], 13, v[30:31]
	v_ashrrev_i32_e32 v27, 31, v26
	v_lshl_add_u64 v[34:35], v[28:29], 0, v[30:31]
	v_lshlrev_b64 v[26:27], 13, v[26:27]
	v_lshl_add_u64 v[42:43], v[28:29], 0, v[26:27]
	global_load_dwordx4 v[26:29], v[34:35], off
	global_load_dwordx4 v[30:33], v[42:43], off
	v_lshlrev_b32_e32 v36, 3, v36
	v_and_b32_e32 v36, 56, v36
	v_add_u32_e32 v42, s15, v40
	v_lshl_add_u64 v[34:35], s[6:7], 0, v[40:41]
	v_lshlrev_b32_e32 v40, 1, v36
	s_movk_i32 s6, 0x84
	v_mul_u32_u24_e32 v39, 0x84, v36
	v_lshl_add_u64 v[36:37], s[8:9], 0, v[40:41]
	v_lshlrev_b32_e32 v40, 2, v38
	v_add3_u32 v39, s15, v39, v40
	v_mul_lo_u32 v40, v38, s6
	s_lshl_b32 s12, s14, 5
	s_lshl_b32 s11, s10, 5
	v_add_u32_e32 v40, v42, v40
	s_mov_b32 s13, s12
	v_mov_b32_e32 v41, v38
	s_branch .LBB0_56

; #define LAS __attribute__((address_space(3)))
; #define TR_LOAD(it_) do { const int kb_ = (it_) / nblk, nb_ = (it_) % nblk; _Pragma("unroll") for (int i = 0; i < 8; ++i) r[i] = *(const f32x4*)(W + (size_t)(kb_ * 64 + 8 * i + (lane >> 3)) * ldw + nb_ * 32 + (lane & 7) * 4); } while (0)
; __device__ __forceinline__ void tr_job(const Ctx& c, int& rot, const float* W, int K, int N, int ldw, bf16_t* WT, int ldt, int row_off) {
;     LAS float* scr = (LAS float*)(c.lds + c.wave * 16384);
;     const int nblk = N / 32, items = (K / 64) * nblk;
;     int first = c.gw - (rot % c.ngw); if (first < 0) first += c.ngw;
;     int lane = c.lane; asm volatile("" : "+v"(lane));
;     f32x4 r[8];
;     ...
;     if (first < items) TR_LOAD(first);
; __device__ __forceinline__ void phase_prologue(KP P, const Ctx& c) {
;     ...
;     for (int m = 0; m < 3; ++m) tr_job(c, rot, P->in[I_RWRKV] + (size_t)m * D * D, D, D, D, (bf16_t*)(ws + WS_RW1), D, m * D);
.LBB0_58:
	s_mul_hi_u32 s6, s22, 0x4800
	s_mul_i32 s6, s6, s21
	s_sub_i32 s6, 0x4800, s6
	s_sub_i32 s7, s6, s21
	s_cmp_ge_u32 s6, s21
	s_cselect_b32 s6, s7, s6
	s_sub_i32 s7, s6, s21
	s_cmp_ge_u32 s6, s21
	s_cselect_b32 s6, s7, s6
	s_sub_i32 s6, s20, s6
	s_ashr_i32 s7, s6, 31
	s_and_b32 s7, s7, s14
	s_add_i32 s6, s7, s6
	v_mov_b32_e32 v36, v1
	s_cmpk_gt_i32 s6, 0x7ff
	s_cbranch_scc1 .LBB0_63
	s_cmpk_eq_i32 s3, 0x100
	s_cbranch_scc1 .LBB0_63
	s_waitcnt lgkmcnt(0)
	s_add_u32 s4, s4, 0x2000000
	s_addc_u32 s5, s5, 0
	s_ashr_i32 s7, s6, 31
	s_lshr_b32 s7, s7, 26
	s_add_i32 s7, s6, s7
	s_andn2_b32 s7, s7, 63
	s_sub_i32 s10, s6, s7
	s_lshl_b32 s10, s10, 5
	s_ashr_i32 s11, s10, 31
	v_ashrrev_i32_e32 v38, 3, v36
	s_lshl_b64 s[10:11], s[10:11], 2
	s_waitcnt vmcnt(5)
	v_add_u32_e32 v26, s7, v38
	s_add_u32 s10, s4, s10
	v_lshlrev_b32_e32 v2, 4, v36
	s_addc_u32 s11, s5, s11
	v_and_b32_e32 v40, 0x70, v2
	v_mov_b32_e32 v41, 0
	v_ashrrev_i32_e32 v27, 31, v26
	v_lshl_add_u64 v[28:29], s[10:11], 0, v[40:41]
	v_lshlrev_b64 v[2:3], 13, v[26:27]
	v_lshl_add_u64 v[10:11], v[28:29], 0, v[2:3]
	v_add_u32_e32 v2, 8, v26
	v_ashrrev_i32_e32 v3, 31, v2
	v_lshlrev_b64 v[2:3], 13, v[2:3]
	v_lshl_add_u64 v[12:13], v[28:29], 0, v[2:3]
	global_load_dwordx4 v[2:5], v[10:11], off
	global_load_dwordx4 v[6:9], v[12:13], off
	v_add_u32_e32 v10, 16, v26
	v_ashrrev_i32_e32 v11, 31, v10
	v_lshlrev_b64 v[10:11], 13, v[10:11]
	v_lshl_add_u64 v[18:19], v[28:29], 0, v[10:11]
	v_add_u32_e32 v10, 24, v26
	v_ashrrev_i32_e32 v11, 31, v10
	v_lshlrev_b64 v[10:11], 13, v[10:11]
	v_lshl_add_u64 v[20:21], v[28:29], 0, v[10:11]
	global_load_dwordx4 v[10:13], v[18:19], off
	global_load_dwordx4 v[14:17], v[20:21], off
	v_add_u32_e32 v18, 32, v26
	v_ashrrev_i32_e32 v19, 31, v18
	v_lshlrev_b64 v[18:19], 13, v[18:19]
	s_waitcnt vmcnt(8)
	v_lshl_add_u64 v[30:31], v[28:29], 0, v[18:19]
	v_add_u32_e32 v18, 40, v26
	v_ashrrev_i32_e32 v19, 31, v18
	v_lshlrev_b64 v[18:19], 13, v[18:19]
	v_lshl_add_u64 v[32:33], v[28:29], 0, v[18:19]
	global_load_dwordx4 v[18:21], v[30:31], off
	global_load_dwordx4 v[22:25], v[32:33], off
	v_add_u32_e32 v30, 48, v26
	v_ashrrev_i32_e32 v31, 31, v30
	v_add_u32_e32 v26, 56, v26
	v_lshlrev_b64 v[30:31], 13, v[30:31]
	v_ashrrev_i32_e32 v27, 31, v26
	v_lshl_add_u64 v[34:35], v[28:29], 0, v[30:31]
	v_lshlrev_b64 v[26:27], 13, v[26:27]
	v_lshl_add_u64 v[42:43], v[28:29], 0, v[26:27]
	global_load_dwordx4 v[26:29], v[34:35], off
	global_load_dwordx4 v[30:33], v[42:43], off
	v_lshlrev_b32_e32 v36, 3, v36
	v_and_b32_e32 v36, 56, v36
	v_add_u32_e32 v42, s15, v40
	v_lshl_add_u64 v[34:35], s[4:5], 0, v[40:41]
	v_lshlrev_b32_e32 v40, 1, v36
	s_movk_i32 s4, 0x84
	v_mul_u32_u24_e32 v39, 0x84, v36
	v_lshl_add_u64 v[36:37], s[8:9], 0, v[40:41]
	v_lshlrev_b32_e32 v40, 2, v38
	v_add3_u32 v39, s15, v39, v40
	v_mul_lo_u32 v40, v38, s4
	s_lshl_b32 s10, s14, 5
	s_lshl_b32 s7, s6, 5
	v_add_u32_e32 v40, v42, v40
	s_mov_b32 s11, s10
	v_mov_b32_e32 v41, v38
	s_branch .LBB0_61

; #define LAS __attribute__((address_space(3)))
; #define LDS_WAIT() asm volatile("s_waitcnt lgkmcnt(0)" ::: "memory")
; #define TR_LOAD(it_) do { const int kb_ = (it_) / nblk, nb_ = (it_) % nblk; _Pragma("unroll") for (int i = 0; i < 8; ++i) r[i] = *(const f32x4*)(W + (size_t)(kb_ * 64 + 8 * i + (lane >> 3)) * ldw + nb_ * 32 + (lane & 7) * 4); } while (0)
; __device__ __forceinline__ void tr_job(const Ctx& c, int& rot, const float* W, int K, int N, int ldw, bf16_t* WT, int ldt, int row_off) {
;     LAS float* scr = (LAS float*)(c.lds + c.wave * 16384);
;     const int nblk = N / 32, items = (K / 64) * nblk;
;     int first = c.gw - (rot % c.ngw); if (first < 0) first += c.ngw;
;     int lane = c.lane; asm volatile("" : "+v"(lane));
;     f32x4 r[8];
;     ...
;     if (first < items) TR_LOAD(first);
;     for (int it = first; it < items; it += c.ngw) { const int kb = it / nblk, nb = it % nblk;
; #pragma unroll
;         for (int i = 0; i < 8; ++i) { LAS float* d = scr + (8 * i + (lane >> 3)) * 33 + (lane & 7) * 4; d[0] = r[i][0]; d[1] = r[i][1]; d[2] = r[i][2]; d[3] = r[i][3]; }
;         if (it + c.ngw < items) TR_LOAD(it + c.ngw);
;         LDS_WAIT(); asm volatile("" ::: "memory");
;         const int cc = lane & 7;
; #pragma unroll
;         for (int j = 0; j < 4; ++j) { const int n = (lane >> 3) + 8 * j; const LAS float* sp = scr + (8 * cc) * 33 + n;
;             u32x4 o; o.x = cvt_pk_bf16(sp[0 * 33], sp[1 * 33]); o.y = cvt_pk_bf16(sp[2 * 33], sp[3 * 33]); o.z = cvt_pk_bf16(sp[4 * 33], sp[5 * 33]); o.w = cvt_pk_bf16(sp[6 * 33], sp[7 * 33]);
;             *(u32x4*)(WT + (size_t)(row_off + nb * 32 + n) * ldt + kb * 64 + 8 * cc) = o; }
;         LDS_WAIT(); asm volatile("" ::: "memory"); }
; __device__ __forceinline__ void phase_prologue(KP P, const Ctx& c) {
;     ...
;     for (int m = 0; m < 3; ++m) tr_job(c, rot, P->in[I_RWRKV] + (size_t)m * D * D, D, D, D, (bf16_t*)(ws + WS_RW1), D, m * D);
.Lcv0_B_done:
	v_readlane_b32 s60, v244, 4
	s_cmpk_lg_i32 s60, 0x100
	s_cbranch_scc1 .Ltta_done
	s_cmp_lt_u32 s2, 32
	s_cbranch_scc1 .Ltta_done
	v_readfirstlane_b32 s63, v0
	s_lshr_b32 s61, s63, 6
	s_sub_i32 s62, s2, 32
	s_lshl_b32 s62, s62, 3
	s_add_i32 s61, s61, s62
	s_load_dwordx2 s[68:69], s[94:95], 0x130
	s_load_dwordx2 s[78:79], s[94:95], 0xa0
	v_and_b32_e32 v102, 63, v0
	v_lshlrev_b32_e32 v103, 2, v102
	v_lshlrev_b32_e32 v104, 12, v102
	s_waitcnt lgkmcnt(0)
.Ltta_loop:
	s_cmp_ge_u32 s61, 0xc00
	s_cbranch_scc1 .Ltta_done
	s_and_b32 s73, s61, 0x3ff
	s_lshr_b32 s71, s73, 5
	s_and_b32 s72, s73, 31
	s_mov_b32 s70, 0x2000
	s_lshl_b32 s73, s71, 19
	s_lshl_b32 s76, s72, 8
	s_add_i32 s73, s73, s76
	s_lshl_b32 s77, s72, 18
	s_lshl_b32 s76, s71, 7
	s_add_i32 s77, s77, s76
	s_lshr_b32 s76, s61, 10
	s_lshl_b32 s86, s76, 24
	s_add_i32 s73, s73, s86
	s_add_u32 s64, s78, s73
	s_addc_u32 s65, s79, 0
	s_lshl_b32 s86, s76, 23
	s_add_i32 s77, s77, s86
	s_add_i32 s77, s77, 0x7c00000
	s_add_u32 s74, s68, s77
	s_addc_u32 s75, s69, 0
.Ltta_go:
	global_load_dword v38, v103, s[64:65] nt
	s_add_u32 s64, s64, s70
	s_addc_u32 s65, s65, 0
	global_load_dword v39, v103, s[64:65] nt
	s_add_u32 s64, s64, s70
	s_addc_u32 s65, s65, 0
	global_load_dword v40, v103, s[64:65] nt
	s_add_u32 s64, s64, s70
	s_addc_u32 s65, s65, 0
	global_load_dword v41, v103, s[64:65] nt
	s_add_u32 s64, s64, s70
	s_addc_u32 s65, s65, 0
	global_load_dword v42, v103, s[64:65] nt
	s_add_u32 s64, s64, s70
	s_addc_u32 s65, s65, 0
	global_load_dword v43, v103, s[64:65] nt
	s_add_u32 s64, s64, s70
	s_addc_u32 s65, s65, 0
	global_load_dword v44, v103, s[64:65] nt
	s_add_u32 s64, s64, s70
	s_addc_u32 s65, s65, 0
	global_load_dword v45, v103, s[64:65] nt
	s_add_u32 s64, s64, s70
	s_addc_u32 s65, s65, 0
	global_load_dword v46, v103, s[64:65] nt
	s_add_u32 s64, s64, s70
	s_addc_u32 s65, s65, 0
	global_load_dword v47, v103, s[64:65] nt
	s_add_u32 s64, s64, s70
	s_addc_u32 s65, s65, 0
	global_load_dword v48, v103, s[64:65] nt
	s_add_u32 s64, s64, s70
	s_addc_u32 s65, s65, 0
	global_load_dword v49, v103, s[64:65] nt
	s_add_u32 s64, s64, s70
	s_addc_u32 s65, s65, 0
	global_load_dword v50, v103, s[64:65] nt
	s_add_u32 s64, s64, s70
	s_addc_u32 s65, s65, 0
	global_load_dword v51, v103, s[64:65] nt
	s_add_u32 s64, s64, s70
	s_addc_u32 s65, s65, 0
	global_load_dword v52, v103, s[64:65] nt
	s_add_u32 s64, s64, s70
	s_addc_u32 s65, s65, 0
	global_load_dword v53, v103, s[64:65] nt
	s_add_u32 s64, s64, s70
	s_addc_u32 s65, s65, 0
	global_load_dword v54, v103, s[64:65] nt
	s_add_u32 s64, s64, s70
	s_addc_u32 s65, s65, 0
	global_load_dword v55, v103, s[64:65] nt
	s_add_u32 s64, s64, s70
	s_addc_u32 s65, s65, 0
	global_load_dword v56, v103, s[64:65] nt
	s_add_u32 s64, s64, s70
	s_addc_u32 s65, s65, 0
	global_load_dword v57, v103, s[64:65] nt
	s_add_u32 s64, s64, s70
	s_addc_u32 s65, s65, 0
	global_load_dword v58, v103, s[64:65] nt
	s_add_u32 s64, s64, s70
	s_addc_u32 s65, s65, 0
	global_load_dword v59, v103, s[64:65] nt
	s_add_u32 s64, s64, s70
	s_addc_u32 s65, s65, 0
	global_load_dword v60, v103, s[64:65] nt
	s_add_u32 s64, s64, s70
	s_addc_u32 s65, s65, 0
	global_load_dword v61, v103, s[64:65] nt
	s_add_u32 s64, s64, s70
	s_addc_u32 s65, s65, 0
	global_load_dword v62, v103, s[64:65] nt
	s_add_u32 s64, s64, s70
	s_addc_u32 s65, s65, 0
	global_load_dword v63, v103, s[64:65] nt
	s_add_u32 s64, s64, s70
	s_addc_u32 s65, s65, 0
	global_load_dword v64, v103, s[64:65] nt
	s_add_u32 s64, s64, s70
	s_addc_u32 s65, s65, 0
	global_load_dword v65, v103, s[64:65] nt
	s_add_u32 s64, s64, s70
	s_addc_u32 s65, s65, 0
	global_load_dword v66, v103, s[64:65] nt
	s_add_u32 s64, s64, s70
	s_addc_u32 s65, s65, 0
	global_load_dword v67, v103, s[64:65] nt
	s_add_u32 s64, s64, s70
	s_addc_u32 s65, s65, 0
	global_load_dword v68, v103, s[64:65] nt
	s_add_u32 s64, s64, s70
	s_addc_u32 s65, s65, 0
	global_load_dword v69, v103, s[64:65] nt
	s_add_u32 s64, s64, s70
	s_addc_u32 s65, s65, 0
	global_load_dword v70, v103, s[64:65] nt
	s_add_u32 s64, s64, s70
	s_addc_u32 s65, s65, 0
	global_load_dword v71, v103, s[64:65] nt
	s_add_u32 s64, s64, s70
	s_addc_u32 s65, s65, 0
	global_load_dword v72, v103, s[64:65] nt
	s_add_u32 s64, s64, s70
	s_addc_u32 s65, s65, 0
	global_load_dword v73, v103, s[64:65] nt
	s_add_u32 s64, s64, s70
	s_addc_u32 s65, s65, 0
	global_load_dword v74, v103, s[64:65] nt
	s_add_u32 s64, s64, s70
	s_addc_u32 s65, s65, 0
	global_load_dword v75, v103, s[64:65] nt
	s_add_u32 s64, s64, s70
	s_addc_u32 s65, s65, 0
	global_load_dword v76, v103, s[64:65] nt
	s_add_u32 s64, s64, s70
	s_addc_u32 s65, s65, 0
	global_load_dword v77, v103, s[64:65] nt
	s_add_u32 s64, s64, s70
	s_addc_u32 s65, s65, 0
	global_load_dword v78, v103, s[64:65] nt
	s_add_u32 s64, s64, s70
	s_addc_u32 s65, s65, 0
	global_load_dword v79, v103, s[64:65] nt
	s_add_u32 s64, s64, s70
	s_addc_u32 s65, s65, 0
	global_load_dword v80, v103, s[64:65] nt
	s_add_u32 s64, s64, s70
	s_addc_u32 s65, s65, 0
	global_load_dword v81, v103, s[64:65] nt
	s_add_u32 s64, s64, s70
	s_addc_u32 s65, s65, 0
	global_load_dword v82, v103, s[64:65] nt
	s_add_u32 s64, s64, s70
	s_addc_u32 s65, s65, 0
	global_load_dword v83, v103, s[64:65] nt
	s_add_u32 s64, s64, s70
	s_addc_u32 s65, s65, 0
	global_load_dword v84, v103, s[64:65] nt
	s_add_u32 s64, s64, s70
	s_addc_u32 s65, s65, 0
	global_load_dword v85, v103, s[64:65] nt
	s_add_u32 s64, s64, s70
	s_addc_u32 s65, s65, 0
	global_load_dword v86, v103, s[64:65] nt
	s_add_u32 s64, s64, s70
	s_addc_u32 s65, s65, 0
	global_load_dword v87, v103, s[64:65] nt
	s_add_u32 s64, s64, s70
	s_addc_u32 s65, s65, 0
	global_load_dword v88, v103, s[64:65] nt
	s_add_u32 s64, s64, s70
	s_addc_u32 s65, s65, 0
	global_load_dword v89, v103, s[64:65] nt
	s_add_u32 s64, s64, s70
	s_addc_u32 s65, s65, 0
	global_load_dword v90, v103, s[64:65] nt
	s_add_u32 s64, s64, s70
	s_addc_u32 s65, s65, 0
	global_load_dword v91, v103, s[64:65] nt
	s_add_u32 s64, s64, s70
	s_addc_u32 s65, s65, 0
	global_load_dword v92, v103, s[64:65] nt
	s_add_u32 s64, s64, s70
	s_addc_u32 s65, s65, 0
	global_load_dword v93, v103, s[64:65] nt
	s_add_u32 s64, s64, s70
	s_addc_u32 s65, s65, 0
	global_load_dword v94, v103, s[64:65] nt
	s_add_u32 s64, s64, s70
	s_addc_u32 s65, s65, 0
	global_load_dword v95, v103, s[64:65] nt
	s_add_u32 s64, s64, s70
	s_addc_u32 s65, s65, 0
	global_load_dword v96, v103, s[64:65] nt
	s_add_u32 s64, s64, s70
	s_addc_u32 s65, s65, 0
	global_load_dword v97, v103, s[64:65] nt
	s_add_u32 s64, s64, s70
	s_addc_u32 s65, s65, 0
	global_load_dword v98, v103, s[64:65] nt
	s_add_u32 s64, s64, s70
	s_addc_u32 s65, s65, 0
	global_load_dword v99, v103, s[64:65] nt
	s_add_u32 s64, s64, s70
	s_addc_u32 s65, s65, 0
	global_load_dword v100, v103, s[64:65] nt
	s_add_u32 s64, s64, s70
	s_addc_u32 s65, s65, 0
	global_load_dword v101, v103, s[64:65] nt
	s_waitcnt vmcnt(0)
; #define LAS __attribute__((address_space(3)))
; #define LDS_WAIT() asm volatile("s_waitcnt lgkmcnt(0)" ::: "memory")
; __device__ __forceinline__ void tr_job(const Ctx& c, int& rot, const float* W, int K, int N, int ldw, bf16_t* WT, int ldt, int row_off) {
;     ...
;         for (int j = 0; j < 4; ++j) { const int n = (lane >> 3) + 8 * j; const LAS float* sp = scr + (8 * cc) * 33 + n;
;             u32x4 o; o.x = cvt_pk_bf16(sp[0 * 33], sp[1 * 33]); o.y = cvt_pk_bf16(sp[2 * 33], sp[3 * 33]); o.z = cvt_pk_bf16(sp[4 * 33], sp[5 * 33]); o.w = cvt_pk_bf16(sp[6 * 33], sp[7 * 33]);
;             *(u32x4*)(WT + (size_t)(row_off + nb * 32 + n) * ldt + kb * 64 + 8 * cc) = o; }
;         LDS_WAIT(); asm volatile("" ::: "memory"); }
;     ...
;     rot += items;
	v_cvt_pk_bf16_f32 v38, v38, v39
	v_cvt_pk_bf16_f32 v39, v40, v41
	v_cvt_pk_bf16_f32 v40, v42, v43
	v_cvt_pk_bf16_f32 v41, v44, v45
	v_cvt_pk_bf16_f32 v42, v46, v47
	v_cvt_pk_bf16_f32 v43, v48, v49
	v_cvt_pk_bf16_f32 v44, v50, v51
	v_cvt_pk_bf16_f32 v45, v52, v53
	v_cvt_pk_bf16_f32 v46, v54, v55
	v_cvt_pk_bf16_f32 v47, v56, v57
	v_cvt_pk_bf16_f32 v48, v58, v59
	v_cvt_pk_bf16_f32 v49, v60, v61
	v_cvt_pk_bf16_f32 v50, v62, v63
	v_cvt_pk_bf16_f32 v51, v64, v65
	v_cvt_pk_bf16_f32 v52, v66, v67
	v_cvt_pk_bf16_f32 v53, v68, v69
	v_cvt_pk_bf16_f32 v54, v70, v71
	v_cvt_pk_bf16_f32 v55, v72, v73
	v_cvt_pk_bf16_f32 v56, v74, v75
	v_cvt_pk_bf16_f32 v57, v76, v77
	v_cvt_pk_bf16_f32 v58, v78, v79
	v_cvt_pk_bf16_f32 v59, v80, v81
	v_cvt_pk_bf16_f32 v60, v82, v83
	v_cvt_pk_bf16_f32 v61, v84, v85
	v_cvt_pk_bf16_f32 v62, v86, v87
	v_cvt_pk_bf16_f32 v63, v88, v89
	v_cvt_pk_bf16_f32 v64, v90, v91
	v_cvt_pk_bf16_f32 v65, v92, v93
	v_cvt_pk_bf16_f32 v66, v94, v95
	v_cvt_pk_bf16_f32 v67, v96, v97
	v_cvt_pk_bf16_f32 v68, v98, v99
	v_cvt_pk_bf16_f32 v69, v100, v101
	global_store_dwordx4 v104, v[38:41], s[74:75]
	global_store_dwordx4 v104, v[42:45], s[74:75] offset:16
	global_store_dwordx4 v104, v[46:49], s[74:75] offset:32
	global_store_dwordx4 v104, v[50:53], s[74:75] offset:48
	global_store_dwordx4 v104, v[54:57], s[74:75] offset:64
	global_store_dwordx4 v104, v[58:61], s[74:75] offset:80
	global_store_dwordx4 v104, v[62:65], s[74:75] offset:96
	global_store_dwordx4 v104, v[66:69], s[74:75] offset:112
	s_nop 1
	s_add_i32 s61, s61, 0x700
	s_branch .Ltta_loop

; #define LAS __attribute__((address_space(3)))
; #define LDS_WAIT() asm volatile("s_waitcnt lgkmcnt(0)" ::: "memory")
; #define TR_LOAD(it_) do { const int kb_ = (it_) / nblk, nb_ = (it_) % nblk; _Pragma("unroll") for (int i = 0; i < 8; ++i) r[i] = *(const f32x4*)(W + (size_t)(kb_ * 64 + 8 * i + (lane >> 3)) * ldw + nb_ * 32 + (lane & 7) * 4); } while (0)
; __device__ __forceinline__ void tr_job(const Ctx& c, int& rot, const float* W, int K, int N, int ldw, bf16_t* WT, int ldt, int row_off) {
;     LAS float* scr = (LAS float*)(c.lds + c.wave * 16384);
;     const int nblk = N / 32, items = (K / 64) * nblk;
;     int first = c.gw - (rot % c.ngw); if (first < 0) first += c.ngw;
;     int lane = c.lane; asm volatile("" : "+v"(lane));
;     f32x4 r[8];
;     ...
;     if (first < items) TR_LOAD(first);
;     for (int it = first; it < items; it += c.ngw) { const int kb = it / nblk, nb = it % nblk;
; #pragma unroll
;         for (int i = 0; i < 8; ++i) { LAS float* d = scr + (8 * i + (lane >> 3)) * 33 + (lane & 7) * 4; d[0] = r[i][0]; d[1] = r[i][1]; d[2] = r[i][2]; d[3] = r[i][3]; }
;         if (it + c.ngw < items) TR_LOAD(it + c.ngw);
;         LDS_WAIT(); asm volatile("" ::: "memory");
;         const int cc = lane & 7;
; #pragma unroll
;         for (int j = 0; j < 4; ++j) { const int n = (lane >> 3) + 8 * j; const LAS float* sp = scr + (8 * cc) * 33 + n;
;             u32x4 o; o.x = cvt_pk_bf16(sp[0 * 33], sp[1 * 33]); o.y = cvt_pk_bf16(sp[2 * 33], sp[3 * 33]); o.z = cvt_pk_bf16(sp[4 * 33], sp[5 * 33]); o.w = cvt_pk_bf16(sp[6 * 33], sp[7 * 33]);
;             *(u32x4*)(WT + (size_t)(row_off + nb * 32 + n) * ldt + kb * 64 + 8 * cc) = o; }
;         LDS_WAIT(); asm volatile("" ::: "memory"); }
; __device__ __forceinline__ void phase_prologue(KP P, const Ctx& c) {
;     ...
;         tr_job(c, rot, P->in[I_RGWIN] + (size_t)j * D * 4096, D, 4096, 4096, (bf16_t*)(ws + WS_RGIN) + (size_t)j * 4096 * D, D, 0);
;         tr_job(c, rot, P->in[I_RGWOUT] + (size_t)j * D * D, D, D, D, (bf16_t*)(ws + WS_RGOUT) + (size_t)j * D * D, D, 0);
.Lj4b_skip:
	v_readlane_b32 s60, v244, 4
	s_cmpk_lg_i32 s60, 0x100
	s_cbranch_scc1 .Lttb_done
	s_cmp_lt_u32 s2, 32
	s_cbranch_scc1 .Lttb_done
	v_readfirstlane_b32 s63, v0
	s_lshr_b32 s61, s63, 6
	s_sub_i32 s62, s2, 32
	s_lshl_b32 s62, s62, 3
	s_add_i32 s61, s61, s62
	s_load_dwordx2 s[68:69], s[94:95], 0x130
	s_load_dwordx2 s[78:79], s[94:95], 0x60
	s_load_dwordx2 s[80:81], s[94:95], 0x90
	v_and_b32_e32 v102, 63, v0
	v_lshlrev_b32_e32 v103, 2, v102
	v_lshlrev_b32_e32 v104, 12, v102
	s_waitcnt lgkmcnt(0)
.Lttb_loop:
	s_cmp_ge_u32 s61, 0xc00
	s_cbranch_scc1 .Lttb_done
	s_cmp_ge_u32 s61, 0x800
	s_cbranch_scc1 .Lttb_out
	s_lshr_b32 s71, s61, 6
	s_and_b32 s72, s61, 63
	s_mov_b32 s70, 0x4000
	s_lshl_b32 s73, s71, 20
	s_lshl_b32 s76, s72, 8
	s_add_i32 s73, s73, s76
	s_add_i32 s73, s73, 0x2000000
	s_add_u32 s64, s78, s73
	s_addc_u32 s65, s79, 0
	s_lshl_b32 s77, s72, 18
	s_lshl_b32 s76, s71, 7
	s_add_i32 s77, s77, s76
	s_add_i32 s77, s77, 0x5400000
	s_add_u32 s74, s68, s77
	s_addc_u32 s75, s69, 0
	s_branch .Lttb_go
.Lttb_out:
	s_and_b32 s73, s61, 0x3ff
	s_lshr_b32 s71, s73, 5
	s_and_b32 s72, s73, 31
	s_mov_b32 s70, 0x2000
	s_lshl_b32 s73, s71, 19
	s_lshl_b32 s76, s72, 8
	s_add_i32 s73, s73, s76
	s_add_i32 s73, s73, 0x1000000
	s_add_u32 s64, s80, s73
	s_addc_u32 s65, s81, 0
	s_lshl_b32 s77, s72, 18
	s_lshl_b32 s76, s71, 7
	s_add_i32 s77, s77, s76
	s_add_i32 s77, s77, 0x7400000
	s_add_u32 s74, s68, s77
	s_addc_u32 s75, s69, 0
